# v23 + nt on P3 token-row loads (tile loop, preheader, step A)
# baseline (speedup 1.0000x reference)
; __device__ __forceinline__ void phase3(const P3Args& A, unsigned char* lds, int tid, int wave, int lane) {
;     ...
;         __syncthreads();
; #pragma unroll 1
;         for (int rep = 0; rep < 8 * REP_P3A; ++rep) {
;             const int task = tid + (rep & 7) * 512, tok = task >> 5, c8 = (task & 31) * 8, t = t0 + tok;
;             const u32x4 pc = *(const u32x4*)(A.Rb + (size_t)t * RW + 1536 + c8);
;             u32x4 pp = (u32x4){0u, 0u, 0u, 0u};
;             if (t % SEQ) pp = *(const u32x4*)(A.Rb + (size_t)(t - 1) * RW + 1536 + c8);
;             const f32x4 m0 = *(const f32x4*)(A.mu + 1536 + c8), m1 = *(const f32x4*)(A.mu + 1536 + c8 + 4);
.LBB0_311:
	s_barrier
	global_load_dwordx4 v[0:3], v[112:113], off offset:16
	global_load_dwordx4 v[4:7], v[112:113], off nt
	s_lshl_b32 s37, s41, 7
	s_mov_b32 s6, 0
	s_branch .LBB0_313

; __device__ __forceinline__ void phase3(const P3Args& A, unsigned char* lds, int tid, int wave, int lane) {
;     ...
;             const int task = tid + (rep & 7) * 512, tok = task >> 5, c8 = (task & 31) * 8, t = t0 + tok;
;             const u32x4 pc = *(const u32x4*)(A.Rb + (size_t)t * RW + 1536 + c8);
;             u32x4 pp = (u32x4){0u, 0u, 0u, 0u};
;             if (t % SEQ) pp = *(const u32x4*)(A.Rb + (size_t)(t - 1) * RW + 1536 + c8);
.LBB0_313:
	v_add_u32_e32 v8, s6, v117
	v_ashrrev_i32_e32 v18, 5, v8
	v_add_u32_e32 v16, s37, v18
	v_mad_i64_i32 v[8:9], s[0:1], v16, s17, v[114:115]
	global_load_dwordx4 v[8:11], v[8:9], off offset:3072 nt
	v_and_b32_e32 v13, 0xfff, v16
	v_mov_b32_e32 v12, 0
	v_cmp_ne_u32_e64 s[0:1], 0, v13
	v_mov_b32_e32 v13, 0
	v_mov_b32_e32 v14, 0
	v_mov_b32_e32 v15, 0
	s_and_saveexec_b64 s[4:5], s[0:1]
	s_cbranch_execz .LBB0_315
	v_add_u32_e32 v12, -1, v16
	v_mad_i64_i32 v[12:13], s[0:1], v12, s17, v[114:115]
	global_load_dwordx4 v[12:15], v[12:13], off offset:3072 nt

; __device__ __forceinline__ void phase3(const P3Args& A, unsigned char* lds, int tid, int wave, int lane) {
;     ...
;         { int zo0; asm volatile("v_mov_b32 %0, 0" : "=v"(zo0)); P3_ROWLOAD(0, lane + zo0); }
.LBB0_321:
	s_waitcnt lgkmcnt(0)
	s_barrier
	v_mov_b32 v0, 0
	s_ashr_i32 s0, s37, 31
	v_add_u32_e32 v0, v0, v109
	s_lshr_b32 s0, s0, 20
	v_lshlrev_b32_e32 v1, 3, v0
	s_add_i32 s0, s37, s0
	v_and_b32_e32 v4, 56, v1
	v_mul_hi_i32 v1, v0, s91
	s_and_b32 s0, s0, 0xfffff000
	v_lshrrev_b32_e32 v2, 31, v1
	v_ashrrev_i32_e32 v1, 6, v1
	s_sub_i32 s6, s37, s0
	s_add_i32 s7, s37, -1
	v_add_u32_e32 v1, v1, v2
	s_cmp_lg_u32 s6, 0
	v_mad_u64_u32 v[2:3], s[0:1], v1, s92, v[0:1]
	s_cselect_b64 s[42:43], -1, 0
	v_cmp_lt_u32_e64 s[4:5], 7, v2
	v_cmp_gt_i32_e64 s[0:1], s93, v0
	s_or_b64 s[4:5], s[42:43], s[4:5]
	s_and_b64 s[4:5], s[0:1], s[4:5]
	v_mov_b32_e32 v40, 0
	v_lshlrev_b32_e32 v110, 1, v4
	v_mov_b32_e32 v48, 0
	v_mov_b32_e32 v49, 0
	v_mov_b32_e32 v50, 0
	v_mov_b32_e32 v51, 0
	s_and_saveexec_b64 s[0:1], s[4:5]
	s_cbranch_execz .LBB0_323
	v_ashrrev_i32_e32 v2, 3, v2
	v_add_u32_e32 v4, s7, v2
	v_mov_b64_e32 v[2:3], s[26:27]
	v_mad_i64_i32 v[2:3], s[4:5], v4, s17, v[2:3]
	v_lshlrev_b32_e32 v4, 9, v1
	v_ashrrev_i32_e32 v5, 31, v4
	v_lshl_add_u64 v[2:3], v[4:5], 1, v[2:3]
	v_lshl_add_u64 v[2:3], s[34:35], 1, v[2:3]
	v_lshl_add_u64 v[2:3], v[2:3], 0, v[110:111]
	global_load_dwordx4 v[48:51], v[2:3], off nt
.LBB0_323:
	s_or_b64 exec, exec, s[0:1]
	v_add_u32_e32 v2, 64, v0
	v_mul_hi_i32 v1, v2, s91
	v_lshrrev_b32_e32 v3, 31, v1
	v_ashrrev_i32_e32 v1, 6, v1
	v_add_u32_e32 v1, v1, v3
	v_mad_u64_u32 v[2:3], s[0:1], v1, s92, v[2:3]
	v_cmp_lt_u32_e64 s[4:5], 7, v2
	v_cmp_gt_i32_e64 s[0:1], s94, v0
	s_or_b64 s[4:5], s[42:43], s[4:5]
	s_and_b64 s[4:5], s[0:1], s[4:5]
	v_mov_b32_e32 v60, 0
	v_mov_b32_e32 v61, 0
	v_mov_b32_e32 v62, 0
	v_mov_b32_e32 v63, 0
	s_and_saveexec_b64 s[0:1], s[4:5]
	s_cbranch_execz .LBB0_325
	v_ashrrev_i32_e32 v2, 3, v2
	v_add_u32_e32 v4, s7, v2
	v_mov_b64_e32 v[2:3], s[26:27]
	v_mad_i64_i32 v[2:3], s[4:5], v4, s17, v[2:3]
	v_lshlrev_b32_e32 v4, 9, v1
	v_ashrrev_i32_e32 v5, 31, v4
	v_lshl_add_u64 v[2:3], v[4:5], 1, v[2:3]
	v_lshl_add_u64 v[2:3], s[34:35], 1, v[2:3]
	v_lshl_add_u64 v[2:3], v[2:3], 0, v[110:111]
	global_load_dwordx4 v[60:63], v[2:3], off nt
.LBB0_325:
	s_or_b64 exec, exec, s[0:1]
	v_add_u32_e32 v2, 0x80, v0
	v_mul_hi_i32 v1, v2, s91
	v_lshrrev_b32_e32 v3, 31, v1
	v_ashrrev_i32_e32 v1, 6, v1
	v_add_u32_e32 v1, v1, v3
	v_mad_u64_u32 v[2:3], s[0:1], v1, s92, v[2:3]
	v_cmp_lt_u32_e64 s[4:5], 7, v2
	v_cmp_gt_i32_e64 s[0:1], s95, v0
	s_or_b64 s[4:5], s[42:43], s[4:5]
	s_and_b64 s[4:5], s[0:1], s[4:5]
	v_mov_b32_e32 v41, 0
	v_mov_b32_e32 v42, 0
	v_mov_b32_e32 v43, 0
	s_and_saveexec_b64 s[0:1], s[4:5]
	s_cbranch_execz .LBB0_327
	v_ashrrev_i32_e32 v2, 3, v2
	v_add_u32_e32 v4, s7, v2
	v_mov_b64_e32 v[2:3], s[26:27]
	v_mad_i64_i32 v[2:3], s[4:5], v4, s17, v[2:3]
	v_lshlrev_b32_e32 v4, 9, v1
	v_ashrrev_i32_e32 v5, 31, v4
	v_lshl_add_u64 v[2:3], v[4:5], 1, v[2:3]
	v_lshl_add_u64 v[2:3], s[34:35], 1, v[2:3]
	v_lshl_add_u64 v[2:3], v[2:3], 0, v[110:111]
	global_load_dwordx4 v[40:43], v[2:3], off nt
.LBB0_327:
	s_or_b64 exec, exec, s[0:1]
	v_add_u32_e32 v2, 0xc0, v0
	v_mul_hi_i32 v1, v2, s91
	v_lshrrev_b32_e32 v3, 31, v1
	v_ashrrev_i32_e32 v1, 6, v1
	v_add_u32_e32 v1, v1, v3
	v_mad_u64_u32 v[2:3], s[0:1], v1, s92, v[2:3]
	v_cmp_lt_u32_e64 s[4:5], 7, v2
	v_cmp_gt_i32_e64 s[0:1], s96, v0
	s_or_b64 s[4:5], s[42:43], s[4:5]
	s_and_b64 s[4:5], s[0:1], s[4:5]
	v_mov_b32_e32 v72, 0
	v_mov_b32_e32 v76, 0
	v_mov_b32_e32 v77, 0
	v_mov_b32_e32 v78, 0
	v_mov_b32_e32 v79, 0
	s_and_saveexec_b64 s[0:1], s[4:5]
	s_cbranch_execz .LBB0_329
	v_ashrrev_i32_e32 v2, 3, v2
	v_add_u32_e32 v4, s7, v2
	v_mov_b64_e32 v[2:3], s[26:27]
	v_mad_i64_i32 v[2:3], s[4:5], v4, s17, v[2:3]
	v_lshlrev_b32_e32 v4, 9, v1
	v_ashrrev_i32_e32 v5, 31, v4
	v_lshl_add_u64 v[2:3], v[4:5], 1, v[2:3]
	v_lshl_add_u64 v[2:3], s[34:35], 1, v[2:3]
	v_lshl_add_u64 v[2:3], v[2:3], 0, v[110:111]
	global_load_dwordx4 v[76:79], v[2:3], off nt
.LBB0_329:
	s_or_b64 exec, exec, s[0:1]
	v_add_u32_e32 v2, 0x100, v0
	v_mul_hi_i32 v1, v2, s91
	v_lshrrev_b32_e32 v3, 31, v1
	v_ashrrev_i32_e32 v1, 6, v1
	v_add_u32_e32 v1, v1, v3
	v_mad_u64_u32 v[2:3], s[0:1], v1, s92, v[2:3]
	v_cmp_lt_u32_e64 s[4:5], 7, v2
	v_cmp_gt_i32_e64 s[0:1], s97, v0
	s_or_b64 s[4:5], s[42:43], s[4:5]
	s_and_b64 s[4:5], s[0:1], s[4:5]
	v_mov_b32_e32 v73, 0
	v_mov_b32_e32 v74, 0
	v_mov_b32_e32 v75, 0
	s_and_saveexec_b64 s[0:1], s[4:5]
	s_cbranch_execz .LBB0_331
	v_ashrrev_i32_e32 v2, 3, v2
	v_add_u32_e32 v4, s7, v2
	v_mov_b64_e32 v[2:3], s[26:27]
	v_mad_i64_i32 v[2:3], s[4:5], v4, s17, v[2:3]
	v_lshlrev_b32_e32 v4, 9, v1
	v_ashrrev_i32_e32 v5, 31, v4
	v_lshl_add_u64 v[2:3], v[4:5], 1, v[2:3]
	v_lshl_add_u64 v[2:3], s[34:35], 1, v[2:3]
	v_lshl_add_u64 v[2:3], v[2:3], 0, v[110:111]
	global_load_dwordx4 v[72:75], v[2:3], off nt
.LBB0_331:
	s_or_b64 exec, exec, s[0:1]
	v_add_u32_e32 v2, 0x140, v0
	v_mul_hi_i32 v1, v2, s91
	v_lshrrev_b32_e32 v3, 31, v1
	v_ashrrev_i32_e32 v1, 6, v1
	v_add_u32_e32 v1, v1, v3
	v_mad_u64_u32 v[2:3], s[0:1], v1, s92, v[2:3]
	v_cmp_lt_u32_e64 s[4:5], 7, v2
	v_cmp_gt_i32_e64 s[0:1], s88, v0
	s_or_b64 s[4:5], s[42:43], s[4:5]
	s_and_b64 s[4:5], s[0:1], s[4:5]
	v_mov_b32_e32 v92, 0
	v_mov_b32_e32 v96, 0
	v_mov_b32_e32 v97, 0
	v_mov_b32_e32 v98, 0
	v_mov_b32_e32 v99, 0
	s_and_saveexec_b64 s[0:1], s[4:5]
	s_cbranch_execz .LBB0_333
	v_ashrrev_i32_e32 v2, 3, v2
	v_add_u32_e32 v4, s7, v2
	v_mov_b64_e32 v[2:3], s[26:27]
	v_mad_i64_i32 v[2:3], s[4:5], v4, s17, v[2:3]
	v_lshlrev_b32_e32 v4, 9, v1
	v_ashrrev_i32_e32 v5, 31, v4
	v_lshl_add_u64 v[2:3], v[4:5], 1, v[2:3]
	v_lshl_add_u64 v[2:3], s[34:35], 1, v[2:3]
	v_lshl_add_u64 v[2:3], v[2:3], 0, v[110:111]
	global_load_dwordx4 v[96:99], v[2:3], off nt
.LBB0_333:
	s_or_b64 exec, exec, s[0:1]
	v_add_u32_e32 v2, 0x180, v0
	v_mul_hi_i32 v1, v2, s91
	v_lshrrev_b32_e32 v3, 31, v1
	v_ashrrev_i32_e32 v1, 6, v1
	v_add_u32_e32 v1, v1, v3
	v_mad_u64_u32 v[2:3], s[0:1], v1, s92, v[2:3]
	v_cmp_lt_u32_e64 s[4:5], 7, v2
	v_cmp_gt_i32_e64 s[0:1], 24, v0
	s_or_b64 s[4:5], s[42:43], s[4:5]
	s_and_b64 s[4:5], s[0:1], s[4:5]
	v_mov_b32_e32 v93, 0
	v_mov_b32_e32 v94, 0
	v_mov_b32_e32 v95, 0
	s_and_saveexec_b64 s[0:1], s[4:5]
	s_cbranch_execz .LBB0_335
	v_ashrrev_i32_e32 v0, 3, v2
	v_add_u32_e32 v0, s7, v0
	v_mov_b64_e32 v[2:3], s[26:27]
	v_mad_i64_i32 v[2:3], s[4:5], v0, s17, v[2:3]
	v_lshlrev_b32_e32 v0, 9, v1
	v_ashrrev_i32_e32 v1, 31, v0
	v_lshl_add_u64 v[0:1], v[0:1], 1, v[2:3]
	v_lshl_add_u64 v[0:1], s[34:35], 1, v[0:1]
	v_lshl_add_u64 v[0:1], v[0:1], 0, v[110:111]
	global_load_dwordx4 v[92:95], v[0:1], off nt

; __device__ __forceinline__ void phase3(const P3Args& A, unsigned char* lds, int tid, int wave, int lane) {
;     ...
;             P3_ROWLOAD((tt < 7) ? tt + 1 : 7, ln);
.LBB0_359:
	s_or_b64 exec, exec, s[6:7]
	s_cmpk_lg_i32 s12, 0x80
	s_cselect_b32 s6, s12, 0x70
	s_add_i32 s6, s6, s37
	s_add_i32 s13, s6, -1
	s_and_b32 s6, s6, 0xff0
	v_add_u32_e32 v41, v194, v110
	s_cmp_lg_u32 s6, 0
	v_mad_u64_u32 v[42:43], s[6:7], v41, s92, v[116:117]
	s_cselect_b64 s[52:53], -1, 0
	v_cmp_lt_u32_e64 s[6:7], 7, v42
	v_and_b32_e32 v48, 56, v195
	s_or_b64 s[6:7], s[6:7], s[52:53]
	s_and_b64 s[14:15], s[50:51], s[6:7]
	v_mov_b32_e32 v40, 0
	v_lshlrev_b32_e32 v110, 1, v48
	v_mov_b32_e32 v48, 0
	v_mov_b32_e32 v49, 0
	v_mov_b32_e32 v50, 0
	v_mov_b32_e32 v51, 0
	s_and_saveexec_b64 s[6:7], s[14:15]
	s_cbranch_execz .LBB0_361
	v_ashrrev_i32_e32 v42, 3, v42
	v_add_u32_e32 v48, s13, v42
	v_mov_b64_e32 v[42:43], s[26:27]
	v_mad_i64_i32 v[42:43], s[14:15], v48, s17, v[42:43]
	v_lshlrev_b32_e32 v48, 9, v41
	v_ashrrev_i32_e32 v49, 31, v48
	v_lshl_add_u64 v[42:43], v[48:49], 1, v[42:43]
	v_lshl_add_u64 v[42:43], s[34:35], 1, v[42:43]
	v_lshl_add_u64 v[42:43], v[42:43], 0, v[110:111]
	global_load_dwordx4 v[48:51], v[42:43], off nt
.LBB0_361:
	s_or_b64 exec, exec, s[6:7]
	v_add_u32_e32 v41, v193, v192
	v_mad_u64_u32 v[42:43], s[6:7], v41, s92, v[128:129]
	v_cmp_lt_u32_e64 s[6:7], 7, v42
	s_or_b64 s[6:7], s[6:7], s[52:53]
	s_and_b64 s[14:15], s[48:49], s[6:7]
	v_mov_b32_e32 v60, 0
	v_mov_b32_e32 v61, 0
	v_mov_b32_e32 v62, 0
	v_mov_b32_e32 v63, 0
	s_and_saveexec_b64 s[6:7], s[14:15]
	s_cbranch_execz .LBB0_363
	v_ashrrev_i32_e32 v42, 3, v42
	v_add_u32_e32 v60, s13, v42
	v_mov_b64_e32 v[42:43], s[26:27]
	v_mad_i64_i32 v[42:43], s[14:15], v60, s17, v[42:43]
	v_lshlrev_b32_e32 v60, 9, v41
	v_ashrrev_i32_e32 v61, 31, v60
	v_lshl_add_u64 v[42:43], v[60:61], 1, v[42:43]
	v_lshl_add_u64 v[42:43], s[34:35], 1, v[42:43]
	v_lshl_add_u64 v[42:43], v[42:43], 0, v[110:111]
	global_load_dwordx4 v[60:63], v[42:43], off nt
.LBB0_363:
	s_or_b64 exec, exec, s[6:7]
	v_add_u32_e32 v74, v191, v190
	v_mad_u64_u32 v[72:73], s[6:7], v74, s92, v[126:127]
	v_cmp_lt_u32_e64 s[6:7], 7, v72
	s_or_b64 s[6:7], s[6:7], s[52:53]
	s_and_b64 s[14:15], s[46:47], s[6:7]
	v_mov_b32_e32 v41, 0
	v_mov_b32_e32 v42, 0
	v_mov_b32_e32 v43, 0
	s_and_saveexec_b64 s[6:7], s[14:15]
	s_cbranch_execz .LBB0_365
	v_ashrrev_i32_e32 v40, 3, v72
	v_add_u32_e32 v42, s13, v40
	v_mov_b64_e32 v[40:41], s[26:27]
	v_mad_i64_i32 v[40:41], s[14:15], v42, s17, v[40:41]
	v_lshlrev_b32_e32 v42, 9, v74
	v_ashrrev_i32_e32 v43, 31, v42
	v_lshl_add_u64 v[40:41], v[42:43], 1, v[40:41]
	v_lshl_add_u64 v[40:41], s[34:35], 1, v[40:41]
	v_lshl_add_u64 v[40:41], v[40:41], 0, v[110:111]
	global_load_dwordx4 v[40:43], v[40:41], off nt
.LBB0_365:
	s_or_b64 exec, exec, s[6:7]
	v_add_u32_e32 v73, v189, v188
	v_mad_u64_u32 v[74:75], s[6:7], v73, s92, v[124:125]
	v_cmp_lt_u32_e64 s[6:7], 7, v74
	s_or_b64 s[6:7], s[6:7], s[52:53]
	s_and_b64 s[14:15], s[44:45], s[6:7]
	v_mov_b32_e32 v72, 0
	v_mov_b32_e32 v76, 0
	v_mov_b32_e32 v77, 0
	v_mov_b32_e32 v78, 0
	v_mov_b32_e32 v79, 0
	s_and_saveexec_b64 s[6:7], s[14:15]
	s_cbranch_execz .LBB0_367
	v_ashrrev_i32_e32 v74, 3, v74
	v_add_u32_e32 v76, s13, v74
	v_mov_b64_e32 v[74:75], s[26:27]
	v_mad_i64_i32 v[74:75], s[14:15], v76, s17, v[74:75]
	v_lshlrev_b32_e32 v76, 9, v73
	v_ashrrev_i32_e32 v77, 31, v76
	v_lshl_add_u64 v[74:75], v[76:77], 1, v[74:75]
	v_lshl_add_u64 v[74:75], s[34:35], 1, v[74:75]
	v_lshl_add_u64 v[74:75], v[74:75], 0, v[110:111]
	global_load_dwordx4 v[76:79], v[74:75], off nt
.LBB0_367:
	s_or_b64 exec, exec, s[6:7]
	v_add_u32_e32 v94, v187, v186
	v_mad_u64_u32 v[92:93], s[6:7], v94, s92, v[122:123]
	v_cmp_lt_u32_e64 s[6:7], 7, v92
	s_or_b64 s[6:7], s[6:7], s[52:53]
	s_and_b64 s[14:15], s[42:43], s[6:7]
	v_mov_b32_e32 v73, 0
	v_mov_b32_e32 v74, 0
	v_mov_b32_e32 v75, 0
	s_and_saveexec_b64 s[6:7], s[14:15]
	s_cbranch_execz .LBB0_369
	v_ashrrev_i32_e32 v72, 3, v92
	v_add_u32_e32 v74, s13, v72
	v_mov_b64_e32 v[72:73], s[26:27]
	v_mad_i64_i32 v[72:73], s[14:15], v74, s17, v[72:73]
	v_lshlrev_b32_e32 v74, 9, v94
	v_ashrrev_i32_e32 v75, 31, v74
	v_lshl_add_u64 v[72:73], v[74:75], 1, v[72:73]
	v_lshl_add_u64 v[72:73], s[34:35], 1, v[72:73]
	v_lshl_add_u64 v[72:73], v[72:73], 0, v[110:111]
	global_load_dwordx4 v[72:75], v[72:73], off nt
.LBB0_369:
	s_or_b64 exec, exec, s[6:7]
	v_add_u32_e32 v93, v185, v184
	v_mad_u64_u32 v[94:95], s[6:7], v93, s92, v[120:121]
	v_cmp_lt_u32_e64 s[6:7], 7, v94
	s_or_b64 s[6:7], s[6:7], s[52:53]
	s_and_b64 s[6:7], s[4:5], s[6:7]
	v_mov_b32_e32 v92, 0
	v_mov_b32_e32 v96, 0
	v_mov_b32_e32 v97, 0
	v_mov_b32_e32 v98, 0
	v_mov_b32_e32 v99, 0
	s_and_saveexec_b64 s[4:5], s[6:7]
	s_cbranch_execz .LBB0_371
	v_ashrrev_i32_e32 v94, 3, v94
	v_add_u32_e32 v96, s13, v94
	v_mov_b64_e32 v[94:95], s[26:27]
	v_mad_i64_i32 v[94:95], s[6:7], v96, s17, v[94:95]
	v_lshlrev_b32_e32 v96, 9, v93
	v_ashrrev_i32_e32 v97, 31, v96
	v_lshl_add_u64 v[94:95], v[96:97], 1, v[94:95]
	v_lshl_add_u64 v[94:95], s[34:35], 1, v[94:95]
	v_lshl_add_u64 v[94:95], v[94:95], 0, v[110:111]
	global_load_dwordx4 v[96:99], v[94:95], off nt
.LBB0_371:
	s_or_b64 exec, exec, s[4:5]
	v_add_u32_e32 v120, v183, v119
	v_mad_u64_u32 v[118:119], s[4:5], v120, s92, v[118:119]
	v_cmp_lt_u32_e64 s[4:5], 7, v118
	s_or_b64 s[4:5], s[4:5], s[52:53]
	s_and_b64 s[4:5], s[0:1], s[4:5]
	v_mov_b32_e32 v93, 0
	v_mov_b32_e32 v94, 0
	v_mov_b32_e32 v95, 0
	s_and_saveexec_b64 s[0:1], s[4:5]
	s_cbranch_execz .LBB0_336
	v_ashrrev_i32_e32 v92, 3, v118
	v_add_u32_e32 v94, s13, v92
	v_mov_b64_e32 v[92:93], s[26:27]
	v_mad_i64_i32 v[92:93], s[4:5], v94, s17, v[92:93]
	v_lshlrev_b32_e32 v94, 9, v120
	v_ashrrev_i32_e32 v95, 31, v94
	v_lshl_add_u64 v[92:93], v[94:95], 1, v[92:93]
	v_lshl_add_u64 v[92:93], s[34:35], 1, v[92:93]
	v_lshl_add_u64 v[92:93], v[92:93], 0, v[110:111]
	global_load_dwordx4 v[92:95], v[92:93], off nt
	s_branch .LBB0_336
